# local-seam verdict made grid-uniform: also requires the eight XCC ids to differ (else every seam stays a full barrier)
# speedup vs baseline: 1.0114x; 1.0069x over previous
; __device__ __forceinline__ unsigned xb_add(unsigned* p, unsigned v) { return __hip_atomic_fetch_add(p, v, __ATOMIC_RELAXED, __HIP_MEMORY_SCOPE_AGENT); }
; __device__ __forceinline__ void xcd_barrier(const XcdBarrier& b) {
;     asm volatile("s_waitcnt vmcnt(0)" ::: "memory");
;     __syncthreads();
;     if (threadIdx.x == 0) {
;         unsigned* bar = b.bar;
;         __builtin_amdgcn_s_waitcnt(0);
;         unsigned nloc = b.st[0], nx = b.st[1];
;         if (nloc == 0u) { xcd_barrier_complete(bar, b.x, nloc, nx); b.st[0] = nloc; b.st[1] = nx; }
;         const unsigned old = xb_add(&bar[XB_XSUB(b.x)], 1u);
;         const unsigned gen = old / nloc;
;         if (old + 1u == (gen + 1u) * nloc) {
.LBB0_1679:
	s_cmp_lt_i32 s57, 5
	s_cbranch_scc1 .LBB0_1733
	s_waitcnt vmcnt(0)
	s_waitcnt vmcnt(0) lgkmcnt(0)
	s_barrier
	s_and_saveexec_b64 s[6:7], s[4:5]
	s_cbranch_execz .LBB0_1732
	buffer_inv sc1
	v_mov_b32_e32 v2, 0x20000
	ds_read_b32 v16, v2 offset:8
	ds_read_b32 v2, v2
	s_lshl_b32 s3, s33, 8
	s_add_u32 s8, s50, s3
	s_addc_u32 s9, s51, 0
	s_waitcnt lgkmcnt(0)
	v_readfirstlane_b32 s10, v16
	v_readfirstlane_b32 s12, v2
	s_nop 1
	s_cmp_eq_u32 s10, 1
	s_cbranch_scc1 .Lseam34_go
	s_cmp_eq_u32 s10, 2
	s_cbranch_scc1 .Lseam34_full
	s_cmp_eq_u32 s12, 0
	s_cbranch_scc1 .Lseam34_full
	v_mov_b32_e32 v0, 0
	global_load_dwordx4 v[6:9], v0, s[50:51] offset:256 sc1
	global_load_dwordx4 v[10:13], v0, s[50:51] offset:272 sc1
	s_waitcnt vmcnt(0)
	v_add_u32_e32 v14, -1, v6
	v_and_b32_e32 v1, v14, v6
	v_min_u32_e32 v15, v6, v7
	v_add_u32_e32 v14, -1, v7
	v_and_or_b32 v1, v14, v7, v1
	v_min_u32_e32 v15, v15, v8
	v_add_u32_e32 v14, -1, v8
	v_and_or_b32 v1, v14, v8, v1
	v_min_u32_e32 v15, v15, v9
	v_add_u32_e32 v14, -1, v9
	v_and_or_b32 v1, v14, v9, v1
	v_min_u32_e32 v15, v15, v10
	v_add_u32_e32 v14, -1, v10
	v_and_or_b32 v1, v14, v10, v1
	v_min_u32_e32 v15, v15, v11
	v_add_u32_e32 v14, -1, v11
	v_and_or_b32 v1, v14, v11, v1
	v_min_u32_e32 v15, v15, v12
	v_add_u32_e32 v14, -1, v12
	v_and_or_b32 v1, v14, v12, v1
	v_min_u32_e32 v15, v15, v13
	v_add_u32_e32 v14, -1, v13
	v_and_or_b32 v1, v14, v13, v1
	v_or_b32_e32 v17, v6, v7
	v_or3_b32 v17, v17, v8, v9
	v_or3_b32 v17, v17, v10, v11
	v_or3_b32 v17, v17, v12, v13
	s_nop 0
	v_readfirstlane_b32 s10, v1
	v_readfirstlane_b32 s13, v15
	v_readfirstlane_b32 s15, v17
	s_nop 1
	s_add_i32 s14, s12, -1
	s_and_b32 s14, s14, s12
	s_or_b32 s10, s10, s14
	s_bcnt1_i32_b32 s15, s15
	s_cmp_lg_u32 s15, 8
	s_cselect_b32 s15, 1, 0
	s_or_b32 s10, s10, s15
	s_cmp_eq_u32 s13, 0
	s_cselect_b32 s13, 1, 0
	s_or_b32 s10, s10, s13
	s_cmpk_lg_i32 s58, 0x100
	s_cselect_b32 s13, 1, 0
	s_or_b32 s10, s10, s13
	s_cmp_eq_u32 s10, 0
	s_cselect_b32 s10, 1, 2
	v_mov_b32_e32 v16, s10
	v_mov_b32_e32 v2, 0x20000
	ds_write_b32 v2, v16 offset:8
	s_cmp_eq_u32 s10, 2
	s_cbranch_scc1 .Lseam34_full

; __device__ __forceinline__ unsigned xb_add(unsigned* p, unsigned v) { return __hip_atomic_fetch_add(p, v, __ATOMIC_RELAXED, __HIP_MEMORY_SCOPE_AGENT); }
; __device__ __forceinline__ void xcd_barrier(const XcdBarrier& b) {
;     asm volatile("s_waitcnt vmcnt(0)" ::: "memory");
;     __syncthreads();
;     if (threadIdx.x == 0) {
;         unsigned* bar = b.bar;
;         __builtin_amdgcn_s_waitcnt(0);
;         unsigned nloc = b.st[0], nx = b.st[1];
;         if (nloc == 0u) { xcd_barrier_complete(bar, b.x, nloc, nx); b.st[0] = nloc; b.st[1] = nx; }
;         const unsigned old = xb_add(&bar[XB_XSUB(b.x)], 1u);
;         const unsigned gen = old / nloc;
;         if (old + 1u == (gen + 1u) * nloc) {
.LBB0_1779:
	s_cmp_lt_i32 s57, 6
	s_cbranch_scc1 .LBB0_1833
	s_waitcnt vmcnt(0)
	s_waitcnt vmcnt(0) lgkmcnt(0)
	s_barrier
	s_and_saveexec_b64 s[6:7], s[4:5]
	s_cbranch_execz .LBB0_1832
	buffer_inv sc1
	v_mov_b32_e32 v2, 0x20000
	ds_read_b32 v16, v2 offset:8
	ds_read_b32 v2, v2
	s_lshl_b32 s3, s33, 8
	s_add_u32 s8, s50, s3
	s_addc_u32 s9, s51, 0
	s_waitcnt lgkmcnt(0)
	v_readfirstlane_b32 s10, v16
	v_readfirstlane_b32 s12, v2
	s_nop 1
	s_cmp_eq_u32 s10, 1
	s_cbranch_scc1 .Lseam45_go
	s_cmp_eq_u32 s10, 2
	s_cbranch_scc1 .Lseam45_full
	s_cmp_eq_u32 s12, 0
	s_cbranch_scc1 .Lseam45_full
	v_mov_b32_e32 v0, 0
	global_load_dwordx4 v[6:9], v0, s[50:51] offset:256 sc1
	global_load_dwordx4 v[10:13], v0, s[50:51] offset:272 sc1
	s_waitcnt vmcnt(0)
	v_add_u32_e32 v14, -1, v6
	v_and_b32_e32 v1, v14, v6
	v_min_u32_e32 v15, v6, v7
	v_add_u32_e32 v14, -1, v7
	v_and_or_b32 v1, v14, v7, v1
	v_min_u32_e32 v15, v15, v8
	v_add_u32_e32 v14, -1, v8
	v_and_or_b32 v1, v14, v8, v1
	v_min_u32_e32 v15, v15, v9
	v_add_u32_e32 v14, -1, v9
	v_and_or_b32 v1, v14, v9, v1
	v_min_u32_e32 v15, v15, v10
	v_add_u32_e32 v14, -1, v10
	v_and_or_b32 v1, v14, v10, v1
	v_min_u32_e32 v15, v15, v11
	v_add_u32_e32 v14, -1, v11
	v_and_or_b32 v1, v14, v11, v1
	v_min_u32_e32 v15, v15, v12
	v_add_u32_e32 v14, -1, v12
	v_and_or_b32 v1, v14, v12, v1
	v_min_u32_e32 v15, v15, v13
	v_add_u32_e32 v14, -1, v13
	v_and_or_b32 v1, v14, v13, v1
	v_or_b32_e32 v17, v6, v7
	v_or3_b32 v17, v17, v8, v9
	v_or3_b32 v17, v17, v10, v11
	v_or3_b32 v17, v17, v12, v13
	s_nop 0
	v_readfirstlane_b32 s10, v1
	v_readfirstlane_b32 s13, v15
	v_readfirstlane_b32 s15, v17
	s_nop 1
	s_add_i32 s14, s12, -1
	s_and_b32 s14, s14, s12
	s_or_b32 s10, s10, s14
	s_bcnt1_i32_b32 s15, s15
	s_cmp_lg_u32 s15, 8
	s_cselect_b32 s15, 1, 0
	s_or_b32 s10, s10, s15
	s_cmp_eq_u32 s13, 0
	s_cselect_b32 s13, 1, 0
	s_or_b32 s10, s10, s13
	s_cmpk_lg_i32 s58, 0x100
	s_cselect_b32 s13, 1, 0
	s_or_b32 s10, s10, s13
	s_cmp_eq_u32 s10, 0
	s_cselect_b32 s10, 1, 2
	v_mov_b32_e32 v16, s10
	v_mov_b32_e32 v2, 0x20000
	ds_write_b32 v2, v16 offset:8
	s_cmp_eq_u32 s10, 2
	s_cbranch_scc1 .Lseam45_full

; __device__ __forceinline__ unsigned xb_add(unsigned* p, unsigned v) { return __hip_atomic_fetch_add(p, v, __ATOMIC_RELAXED, __HIP_MEMORY_SCOPE_AGENT); }
; __device__ __forceinline__ void xcd_barrier(const XcdBarrier& b) {
;     asm volatile("s_waitcnt vmcnt(0)" ::: "memory");
;     __syncthreads();
;     if (threadIdx.x == 0) {
;         unsigned* bar = b.bar;
;         __builtin_amdgcn_s_waitcnt(0);
;         unsigned nloc = b.st[0], nx = b.st[1];
;         if (nloc == 0u) { xcd_barrier_complete(bar, b.x, nloc, nx); b.st[0] = nloc; b.st[1] = nx; }
;         const unsigned old = xb_add(&bar[XB_XSUB(b.x)], 1u);
;         const unsigned gen = old / nloc;
;         if (old + 1u == (gen + 1u) * nloc) {
.LBB0_1904:
	s_cmp_lt_i32 s57, 7
	s_cbranch_scc1 .LBB0_1958
	s_waitcnt vmcnt(0)
	s_waitcnt lgkmcnt(0)
	s_barrier
	s_and_saveexec_b64 s[6:7], s[4:5]
	s_cbranch_execz .LBB0_1957
	buffer_inv sc1
	v_mov_b32_e32 v2, 0x20000
	ds_read_b32 v16, v2 offset:8
	ds_read_b32 v2, v2
	s_lshl_b32 s3, s33, 8
	s_add_u32 s8, s50, s3
	s_addc_u32 s9, s51, 0
	s_waitcnt lgkmcnt(0)
	v_readfirstlane_b32 s10, v16
	v_readfirstlane_b32 s12, v2
	s_nop 1
	s_cmp_eq_u32 s10, 1
	s_cbranch_scc1 .Lseam56_go
	s_cmp_eq_u32 s10, 2
	s_cbranch_scc1 .Lseam56_full
	s_cmp_eq_u32 s12, 0
	s_cbranch_scc1 .Lseam56_full
	v_mov_b32_e32 v0, 0
	global_load_dwordx4 v[6:9], v0, s[50:51] offset:256 sc1
	global_load_dwordx4 v[10:13], v0, s[50:51] offset:272 sc1
	s_waitcnt vmcnt(0)
	v_add_u32_e32 v14, -1, v6
	v_and_b32_e32 v1, v14, v6
	v_min_u32_e32 v15, v6, v7
	v_add_u32_e32 v14, -1, v7
	v_and_or_b32 v1, v14, v7, v1
	v_min_u32_e32 v15, v15, v8
	v_add_u32_e32 v14, -1, v8
	v_and_or_b32 v1, v14, v8, v1
	v_min_u32_e32 v15, v15, v9
	v_add_u32_e32 v14, -1, v9
	v_and_or_b32 v1, v14, v9, v1
	v_min_u32_e32 v15, v15, v10
	v_add_u32_e32 v14, -1, v10
	v_and_or_b32 v1, v14, v10, v1
	v_min_u32_e32 v15, v15, v11
	v_add_u32_e32 v14, -1, v11
	v_and_or_b32 v1, v14, v11, v1
	v_min_u32_e32 v15, v15, v12
	v_add_u32_e32 v14, -1, v12
	v_and_or_b32 v1, v14, v12, v1
	v_min_u32_e32 v15, v15, v13
	v_add_u32_e32 v14, -1, v13
	v_and_or_b32 v1, v14, v13, v1
	v_or_b32_e32 v17, v6, v7
	v_or3_b32 v17, v17, v8, v9
	v_or3_b32 v17, v17, v10, v11
	v_or3_b32 v17, v17, v12, v13
	s_nop 0
	v_readfirstlane_b32 s10, v1
	v_readfirstlane_b32 s13, v15
	v_readfirstlane_b32 s15, v17
	s_nop 1
	s_add_i32 s14, s12, -1
	s_and_b32 s14, s14, s12
	s_or_b32 s10, s10, s14
	s_bcnt1_i32_b32 s15, s15
	s_cmp_lg_u32 s15, 8
	s_cselect_b32 s15, 1, 0
	s_or_b32 s10, s10, s15
	s_cmp_eq_u32 s13, 0
	s_cselect_b32 s13, 1, 0
	s_or_b32 s10, s10, s13
	s_cmpk_lg_i32 s58, 0x100
	s_cselect_b32 s13, 1, 0
	s_or_b32 s10, s10, s13
	s_cmp_eq_u32 s10, 0
	s_cselect_b32 s10, 1, 2
	v_mov_b32_e32 v16, s10
	v_mov_b32_e32 v2, 0x20000
	ds_write_b32 v2, v16 offset:8
	s_cmp_eq_u32 s10, 2
	s_cbranch_scc1 .Lseam56_full

; __device__ __forceinline__ unsigned xb_add(unsigned* p, unsigned v) { return __hip_atomic_fetch_add(p, v, __ATOMIC_RELAXED, __HIP_MEMORY_SCOPE_AGENT); }
; __device__ __forceinline__ void xcd_barrier(const XcdBarrier& b) {
;     asm volatile("s_waitcnt vmcnt(0)" ::: "memory");
;     __syncthreads();
;     if (threadIdx.x == 0) {
;         unsigned* bar = b.bar;
;         __builtin_amdgcn_s_waitcnt(0);
;         unsigned nloc = b.st[0], nx = b.st[1];
;         if (nloc == 0u) { xcd_barrier_complete(bar, b.x, nloc, nx); b.st[0] = nloc; b.st[1] = nx; }
;         const unsigned old = xb_add(&bar[XB_XSUB(b.x)], 1u);
;         const unsigned gen = old / nloc;
;         if (old + 1u == (gen + 1u) * nloc) {
.LBB0_2222:
	s_cmp_lt_i32 s57, 10
	s_cbranch_scc1 .LBB0_2276
	s_waitcnt vmcnt(0)
	s_barrier
	s_and_saveexec_b64 s[6:7], s[4:5]
	s_cbranch_execz .LBB0_2275
	buffer_inv sc1
	v_mov_b32_e32 v2, 0x20000
	ds_read_b32 v16, v2 offset:8
	ds_read_b32 v2, v2
	s_lshl_b32 s3, s33, 8
	s_add_u32 s8, s50, s3
	s_addc_u32 s9, s51, 0
	s_waitcnt lgkmcnt(0)
	v_readfirstlane_b32 s10, v16
	v_readfirstlane_b32 s12, v2
	s_nop 1
	s_cmp_eq_u32 s10, 1
	s_cbranch_scc1 .Lseam89_go
	s_cmp_eq_u32 s10, 2
	s_cbranch_scc1 .Lseam89_full
	s_cmp_eq_u32 s12, 0
	s_cbranch_scc1 .Lseam89_full
	v_mov_b32_e32 v0, 0
	global_load_dwordx4 v[6:9], v0, s[50:51] offset:256 sc1
	global_load_dwordx4 v[10:13], v0, s[50:51] offset:272 sc1
	s_waitcnt vmcnt(0)
	v_add_u32_e32 v14, -1, v6
	v_and_b32_e32 v1, v14, v6
	v_min_u32_e32 v15, v6, v7
	v_add_u32_e32 v14, -1, v7
	v_and_or_b32 v1, v14, v7, v1
	v_min_u32_e32 v15, v15, v8
	v_add_u32_e32 v14, -1, v8
	v_and_or_b32 v1, v14, v8, v1
	v_min_u32_e32 v15, v15, v9
	v_add_u32_e32 v14, -1, v9
	v_and_or_b32 v1, v14, v9, v1
	v_min_u32_e32 v15, v15, v10
	v_add_u32_e32 v14, -1, v10
	v_and_or_b32 v1, v14, v10, v1
	v_min_u32_e32 v15, v15, v11
	v_add_u32_e32 v14, -1, v11
	v_and_or_b32 v1, v14, v11, v1
	v_min_u32_e32 v15, v15, v12
	v_add_u32_e32 v14, -1, v12
	v_and_or_b32 v1, v14, v12, v1
	v_min_u32_e32 v15, v15, v13
	v_add_u32_e32 v14, -1, v13
	v_and_or_b32 v1, v14, v13, v1
	v_or_b32_e32 v17, v6, v7
	v_or3_b32 v17, v17, v8, v9
	v_or3_b32 v17, v17, v10, v11
	v_or3_b32 v17, v17, v12, v13
	s_nop 0
	v_readfirstlane_b32 s10, v1
	v_readfirstlane_b32 s13, v15
	v_readfirstlane_b32 s15, v17
	s_nop 1
	s_add_i32 s14, s12, -1
	s_and_b32 s14, s14, s12
	s_or_b32 s10, s10, s14
	s_bcnt1_i32_b32 s15, s15
	s_cmp_lg_u32 s15, 8
	s_cselect_b32 s15, 1, 0
	s_or_b32 s10, s10, s15
	s_cmp_eq_u32 s13, 0
	s_cselect_b32 s13, 1, 0
	s_or_b32 s10, s10, s13
	s_cmpk_lg_i32 s58, 0x100
	s_cselect_b32 s13, 1, 0
	s_or_b32 s10, s10, s13
	s_cmp_eq_u32 s10, 0
	s_cselect_b32 s10, 1, 2
	v_mov_b32_e32 v16, s10
	v_mov_b32_e32 v2, 0x20000
	ds_write_b32 v2, v16 offset:8
	s_cmp_eq_u32 s10, 2
	s_cbranch_scc1 .Lseam89_full

; __device__ __forceinline__ unsigned xb_add(unsigned* p, unsigned v) { return __hip_atomic_fetch_add(p, v, __ATOMIC_RELAXED, __HIP_MEMORY_SCOPE_AGENT); }
; __device__ __forceinline__ void xcd_barrier(const XcdBarrier& b) {
;     asm volatile("s_waitcnt vmcnt(0)" ::: "memory");
;     __syncthreads();
;     if (threadIdx.x == 0) {
;         unsigned* bar = b.bar;
;         __builtin_amdgcn_s_waitcnt(0);
;         unsigned nloc = b.st[0], nx = b.st[1];
;         if (nloc == 0u) { xcd_barrier_complete(bar, b.x, nloc, nx); b.st[0] = nloc; b.st[1] = nx; }
;         const unsigned old = xb_add(&bar[XB_XSUB(b.x)], 1u);
;         const unsigned gen = old / nloc;
;         if (old + 1u == (gen + 1u) * nloc) {
.LBB0_2546:
	s_cmp_lt_i32 s57, 13
	s_cbranch_scc1 .LBB0_2600
	s_waitcnt vmcnt(0)
	s_waitcnt lgkmcnt(0)
	s_barrier
	s_and_saveexec_b64 s[6:7], s[4:5]
	s_cbranch_execz .LBB0_2599
	buffer_inv sc1
	v_mov_b32_e32 v2, 0x20000
	ds_read_b32 v16, v2 offset:8
	ds_read_b32 v2, v2
	s_lshl_b32 s3, s33, 8
	s_add_u32 s8, s50, s3
	s_addc_u32 s9, s51, 0
	s_waitcnt lgkmcnt(0)
	v_readfirstlane_b32 s10, v16
	v_readfirstlane_b32 s12, v2
	s_nop 1
	s_cmp_eq_u32 s10, 1
	s_cbranch_scc1 .Lseam1112_go
	s_cmp_eq_u32 s10, 2
	s_cbranch_scc1 .Lseam1112_full
	s_cmp_eq_u32 s12, 0
	s_cbranch_scc1 .Lseam1112_full
	v_mov_b32_e32 v0, 0
	global_load_dwordx4 v[6:9], v0, s[50:51] offset:256 sc1
	global_load_dwordx4 v[10:13], v0, s[50:51] offset:272 sc1
	s_waitcnt vmcnt(0)
	v_add_u32_e32 v14, -1, v6
	v_and_b32_e32 v1, v14, v6
	v_min_u32_e32 v15, v6, v7
	v_add_u32_e32 v14, -1, v7
	v_and_or_b32 v1, v14, v7, v1
	v_min_u32_e32 v15, v15, v8
	v_add_u32_e32 v14, -1, v8
	v_and_or_b32 v1, v14, v8, v1
	v_min_u32_e32 v15, v15, v9
	v_add_u32_e32 v14, -1, v9
	v_and_or_b32 v1, v14, v9, v1
	v_min_u32_e32 v15, v15, v10
	v_add_u32_e32 v14, -1, v10
	v_and_or_b32 v1, v14, v10, v1
	v_min_u32_e32 v15, v15, v11
	v_add_u32_e32 v14, -1, v11
	v_and_or_b32 v1, v14, v11, v1
	v_min_u32_e32 v15, v15, v12
	v_add_u32_e32 v14, -1, v12
	v_and_or_b32 v1, v14, v12, v1
	v_min_u32_e32 v15, v15, v13
	v_add_u32_e32 v14, -1, v13
	v_and_or_b32 v1, v14, v13, v1
	v_or_b32_e32 v17, v6, v7
	v_or3_b32 v17, v17, v8, v9
	v_or3_b32 v17, v17, v10, v11
	v_or3_b32 v17, v17, v12, v13
	s_nop 0
	v_readfirstlane_b32 s10, v1
	v_readfirstlane_b32 s13, v15
	v_readfirstlane_b32 s15, v17
	s_nop 1
	s_add_i32 s14, s12, -1
	s_and_b32 s14, s14, s12
	s_or_b32 s10, s10, s14
	s_bcnt1_i32_b32 s15, s15
	s_cmp_lg_u32 s15, 8
	s_cselect_b32 s15, 1, 0
	s_or_b32 s10, s10, s15
	s_cmp_eq_u32 s13, 0
	s_cselect_b32 s13, 1, 0
	s_or_b32 s10, s10, s13
	s_cmpk_lg_i32 s58, 0x100
	s_cselect_b32 s13, 1, 0
	s_or_b32 s10, s10, s13
	s_cmp_eq_u32 s10, 0
	s_cselect_b32 s10, 1, 2
	v_mov_b32_e32 v16, s10
	v_mov_b32_e32 v2, 0x20000
	ds_write_b32 v2, v16 offset:8
	s_cmp_eq_u32 s10, 2
	s_cbranch_scc1 .Lseam1112_full
